# attention unit remap: the 16 workgroups of one (batch,head) now sit on one XCD (it = (bx&7)*32 + bx>>3) so K/V tiles are shared in that XCD's L2
# speedup vs baseline: 1.0098x; 1.0098x over previous
.LBB0_625:
	s_and_b64 vcc, exec, s[2:3]
	s_cbranch_vccz .LBB0_715
	s_add_u32 s33, s88, 0x4000000
	s_addc_u32 s36, s89, 0
	s_add_u32 s37, s90, 0x15400000
	s_addc_u32 s38, s91, 0
	s_add_u32 s39, s90, 0x18400000
	s_addc_u32 s34, s91, 0
	s_add_i32 s2, s68, s82
	s_cmpk_lt_i32 s2, 0x800
	s_cselect_b64 s[0:1], -1, 0
	v_writelane_b32 v246, s0, 59
	s_waitcnt lgkmcnt(1)
	v_max_f32_e32 v0, v208, v208
	v_max_f32_e32 v1, v206, v206
	v_writelane_b32 v246, s1, 60
	s_mul_i32 s0, s68, 0x4100
	s_add_i32 s0, s0, 0
	v_writelane_b32 v246, s0, 61
	s_add_u32 s0, s90, 0x1a400000
	v_writelane_b32 v246, s0, 62
	s_addc_u32 s0, s91, 0
	v_writelane_b32 v246, s0, 63
	s_and_b32 s53, s89, 0xffff
	v_readlane_b32 s0, v246, 36
	v_readlane_b32 s1, v246, 37
	s_and_b32 s13, s1, 0xffff
	s_mov_b32 s12, s0
	s_add_u32 s0, s90, 0x1500000
	s_addc_u32 s1, s91, 0
	v_writelane_b32 v245, s0, 0
	v_max_f32_e32 v0, v1, v0
	s_waitcnt lgkmcnt(0)
	v_max_f32_e32 v1, v209, v209
	v_writelane_b32 v245, s1, 1
	s_add_u32 s0, s90, 0x4100000
	s_addc_u32 s1, s91, 0
	v_writelane_b32 v245, s0, 2
	v_max_f32_e32 v2, v207, v207
	v_max_f32_e32 v1, v2, v1
	v_writelane_b32 v245, s1, 3
	s_add_u32 s0, s90, 0x5700000
	s_addc_u32 s1, s91, 0
	v_writelane_b32 v245, s0, 4
	s_cmpk_lt_i32 s2, 0x2500
	v_mul_f32_e32 v0, 0xc19fecaf, v0
	v_writelane_b32 v245, s1, 5
	s_cselect_b64 s[0:1], -1, 0
	v_writelane_b32 v245, s0, 6
	v_mul_f32_e32 v213, v0, v1
	s_mov_b32 s15, 0x20000
	v_writelane_b32 v245, s1, 7
	s_add_i32 s0, s2, 0xbe0
	v_writelane_b32 v245, s0, 8
	v_writelane_b32 v245, s2, 9
	s_add_i32 s0, s2, 0xffffe600
	v_writelane_b32 v245, s0, 10
	v_writelane_b32 v245, s33, 11
	v_writelane_b32 v245, s36, 12
	v_writelane_b32 v245, s37, 13
	v_writelane_b32 v245, s38, 14
	s_brev_b32 s14, -2
	s_mov_b32 s52, s88
	s_mov_b64 s[2:3], 0
	s_movk_i32 s35, 0xff
	s_movk_i32 s40, 0xc00
	v_mov_b32_e32 v1, 0
	s_movk_i32 s41, 0x190
	s_movk_i32 s42, 0xbf
	v_mov_b32_e32 v214, 0xffffff80
	v_not_b32_e32 v215, 63
	s_movk_i32 s43, 0xaab
	v_mov_b32_e32 v216, 0x358637bd
	s_mov_b32 s54, 0x800000
	s_mov_b64 s[44:45], 0x200000
	s_mov_b32 s46, 0x2aaaaaab
	s_movk_i32 s47, 0x2000
	s_movk_i32 s48, 0x4000
	s_movk_i32 s49, 0xc000
	s_mov_b32 s50, 0x100000
	s_movk_i32 s51, 0x90
	s_movk_i32 s55, 0x6000
	s_mov_b32 s56, 0x8000
	s_mov_b32 s57, 0xa000
	s_movk_i32 s58, 0x80
	s_mov_b32 s59, 0x100080
	s_mov_b64 s[60:61], 0x1a400800
	v_mov_b32_e32 v217, 4
	v_mov_b32_e32 v218, 24
	v_mov_b32_e32 v219, 0xf300
	v_mov_b32_e32 v220, 0x14400
	v_mov_b32_e32 v221, 0x19500
	v_mov_b32_e32 v222, 0x1e600
	v_mov_b32_e32 v223, 0x410
	v_mov_b32_e32 v224, 0x820
	v_mov_b32_e32 v225, 0xc30
	v_mov_b32_e32 v226, 0x1040
	s_and_b32 s84, s64, 7
	s_lshl_b32 s84, s84, 5
	s_lshr_b32 s98, s64, 3
	s_or_b32 s84, s84, s98
	v_readlane_b32 s16, v246, 20
	v_writelane_b32 v245, s39, 15
	v_readlane_b32 s17, v246, 21
	v_readlane_b32 s18, v246, 22
	v_readlane_b32 s19, v246, 23
	v_readlane_b32 s20, v246, 24
	v_readlane_b32 s21, v246, 25
	v_readlane_b32 s22, v246, 26
	v_readlane_b32 s23, v246, 27
	v_readlane_b32 s24, v246, 28
	v_readlane_b32 s25, v246, 29
	v_readlane_b32 s26, v246, 30
	v_readlane_b32 s27, v246, 31
	v_readlane_b32 s28, v246, 32
	v_readlane_b32 s29, v246, 33
	v_readlane_b32 s30, v246, 34
	v_readlane_b32 s31, v246, 35
	v_writelane_b32 v245, s34, 16
	s_branch .LBB0_628
